# attention LDS-DMA pieces placed later in the odd step (after the PV MFMAs of block a, in VALU-only gaps)
# speedup vs baseline: 1.0079x; 1.0079x over previous
; #define LAS __attribute__((address_space(3)))
; __device__ __forceinline__ void attn_unit2(LAS unsigned char* lds, const bf16_t* __restrict__ Q, const bf16_t* __restrict__ KN, const bf16_t* __restrict__ KPE, ...
;     ...
;         SOFTMAX2(sa0, sa1, ma, la, oa0, oa1, pa);
;         SOFTMAX2(sb0, sb1, mb, lb, ob0, ob1, pb);
;     ...
;         const LAS unsigned char* va = lds + sc + va_off;
; #pragma unroll
;         for (int st = 0; st < 4; ++st) {
;             const bf16x8 v0 = *(const LAS bf16x8*)(va + st * 32);
;             const bf16x8 v1 = *(const LAS bf16x8*)(va + 32 * VROW + st * 32);
;             const bf16x8 fa = __builtin_bit_cast(bf16x8, pa[st]), fb = __builtin_bit_cast(bf16x8, pb[st]);
;             oa0 = __builtin_amdgcn_mfma_f32_32x32x16_bf16(v0, fa, oa0, 0, 0, 0);
;             oa1 = __builtin_amdgcn_mfma_f32_32x32x16_bf16(v1, fa, oa1, 0, 0, 0);
;             ob0 = __builtin_amdgcn_mfma_f32_32x32x16_bf16(v0, fb, ob0, 0, 0, 0);
;             ob1 = __builtin_amdgcn_mfma_f32_32x32x16_bf16(v1, fb, ob1, 0, 0, 0);
;         }
;         __builtin_amdgcn_sched_barrier(0);
;         __syncthreads();
.Lat_back_bE:
	v_add_f32_e32 v193, v193, v230
	v_cvt_pk_bf16_f32 v80, v80, v81
	v_cvt_pk_bf16_f32 v81, v82, v83
	v_mfma_f32_32x32x16_bf16 v[112:127], v[220:223], v[174:177], v[112:127]
	v_cvt_pk_bf16_f32 v82, v84, v85
	v_cvt_pk_bf16_f32 v83, v86, v87
	v_cvt_pk_bf16_f32 v84, v88, v89
	v_mfma_f32_32x32x16_bf16 v[112:127], v[240:243], v[248:251], v[112:127]
	v_cvt_pk_bf16_f32 v85, v90, v91
	v_cvt_pk_bf16_f32 v86, v92, v93
	v_cvt_pk_bf16_f32 v87, v94, v95
	s_waitcnt vmcnt(0)
	s_barrier
	s_cmp_lt_u32 s27, 2
	s_cselect_b32 s14, s10, s11
	s_add_i32 s14, s14, s24
	v_add3_u32 v224, s26, v183, v128
	ds_read_b128 v[212:215], v224 offset:0
	ds_read_b128 v[216:219], v224 offset:32
	ds_read_b128 v[220:223], v224 offset:64
	v_mfma_f32_32x32x16_bf16 v[16:31], v[196:199], v[64:67], v[16:31]
	v_exp_f32_e32 v96, v96
	v_exp_f32_e32 v97, v97
	v_exp_f32_e32 v98, v98
	v_exp_f32_e32 v99, v99
	v_mfma_f32_32x32x16_bf16 v[48:63], v[200:203], v[64:67], v[48:63]
	v_exp_f32_e32 v100, v100
	v_exp_f32_e32 v101, v101
	v_add_f32_e32 v230, v96, v97
	v_exp_f32_e32 v102, v102
	v_mfma_f32_32x32x16_bf16 v[16:31], v[204:207], v[68:71], v[16:31]
	v_exp_f32_e32 v103, v103
	v_add_f32_e32 v231, v98, v99
	v_exp_f32_e32 v104, v104
	v_exp_f32_e32 v105, v105
	v_mfma_f32_32x32x16_bf16 v[48:63], v[208:211], v[68:71], v[48:63]
	v_add_f32_e32 v230, v230, v100
	v_add_f32_e32 v231, v231, v101
	s_cmpk_gt_u32 s27, 0x81
	s_cbranch_scc1 .Lat_dmaL_0
	s_and_b64 vcc, exec, s[4:5]
	s_cbranch_vccnz .Lat_dmaL_0
	v_mad_u64_u32 v[234:235], s[16:17], v182, s14, v[180:181]
	s_add_i32 m0, s25, s19
	s_nop 0
	global_load_lds_dwordx4 v[234:235], off
.Lat_dmaL_0:
	v_exp_f32_e32 v106, v106
	v_exp_f32_e32 v107, v107
	v_add_f32_e32 v230, v230, v102
	v_add_f32_e32 v231, v231, v103
	v_mfma_f32_32x32x16_bf16 v[32:47], v[196:199], v[80:83], v[32:47]
	v_exp_f32_e32 v108, v108
	v_exp_f32_e32 v109, v109
	s_cmpk_gt_u32 s27, 0x81
	s_cbranch_scc1 .Lat_dmaL_1
	s_and_b64 vcc, exec, s[6:7]
	s_cbranch_vccnz .Lat_dmaL_1
	v_mad_u64_u32 v[234:235], s[16:17], v186, s14, v[184:185]
	s_add_i32 m0, s25, s20
	s_nop 0
	global_load_lds_dwordx4 v[234:235], off
.Lat_dmaL_1:
	v_add_f32_e32 v230, v230, v104
	v_add_f32_e32 v231, v231, v105
	v_mfma_f32_32x32x16_bf16 v[0:15], v[200:203], v[80:83], v[0:15]
	v_exp_f32_e32 v110, v110
	v_exp_f32_e32 v111, v111
	v_add_f32_e32 v230, v230, v106
	v_add_f32_e32 v231, v231, v107
	v_mfma_f32_32x32x16_bf16 v[32:47], v[204:207], v[84:87], v[32:47]
	v_add_f32_e32 v230, v230, v108
	s_cmpk_gt_u32 s27, 0x81
	s_cbranch_scc1 .Lat_dmaL_2
	s_and_b64 vcc, exec, s[8:9]
	s_cbranch_vccnz .Lat_dmaL_2
	v_mad_u64_u32 v[234:235], s[16:17], v190, s14, v[188:189]
	s_add_i32 m0, s25, s21
	s_nop 0
	global_load_lds_dwordx4 v[234:235], off
.Lat_dmaL_2:
	v_add_f32_e32 v231, v231, v109
	v_add_f32_e32 v230, v230, v110
	v_add_f32_e32 v231, v231, v111
	v_mfma_f32_32x32x16_bf16 v[0:15], v[208:211], v[84:87], v[0:15]
	v_add_f32_e32 v230, v230, v231
	v_add3_u32 v225, s34, v187, v128
	ds_read_b128 v[196:199], v225 offset:13376
	ds_read_b128 v[200:203], v225 offset:17984
	ds_read_b128 v[204:207], v225 offset:13408
	ds_read_b128 v[208:211], v225 offset:18016
	v_cmp_lt_f32_e32 vcc, 0x45800000, v230
	s_cbranch_vccnz .Lat_resc_aO
